# P8 unit boundary: role A hoists next unit first L slot ahead of epilogue, role B defers its last end-of-C barrier past epilogue+header (no alignment bubbles)
# baseline (speedup 1.0000x reference)
;     __host__ __device__ bool next(int i, Unit& u) const { const int L = i * G + c; if (L >= n) return false; u.pm = L; u.pn = L >> 2; return true; }
; #define PG8_STAGE(bufoff, gbase, voff) do { _Pragma("unroll") for (int _i = 0; _i < 2; ++_i) \
;         __builtin_amdgcn_global_load_lds((const unsigned*)((const char*)(gbase) + (voff)[_i]), (PG8_LAS unsigned*)(lds + (bufoff) + ldsw + _i * 8192), 16, 0, 0); } while (0)
; #define PG8_LDA(dst, b, h) do { _Pragma("unroll") for (int m = 0; m < 4; ++m) _Pragma("unroll") for (int k = 0; k < 2; ++k) dst[m][k] = *(const PG8_LAS bf16x8*)(lds + PG8_SA(b, h) + aoff + m * 2048 + k * 1024); } while (0)
; #define PG8_LDB(dst, b, h) do { _Pragma("unroll") for (int n = 0; n < 2; ++n) _Pragma("unroll") for (int k = 0; k < 2; ++k) dst[n][k] = *(const PG8_LAS bf16x8*)(lds + PG8_SB(b, h) + boff + n * 2048 + k * 1024); } while (0)
; template <class Epi, class Sched, bool ALIGN_EPI>
; __device__ __forceinline__ void gemm_phase(PG8_LAS unsigned char* lds, const Gemm g, const Sched& S, const Epi& E) {
;     ...
;         const bool has_next = S.next(ui + 1, nxt);
;         const size_t tail_ = has_next ? 0 : tailoff; const char* nA = (has_next ? (const char*)g.A + (size_t)nxt.pm * tstepA : cA) + (has_next ? 0 : tailoffA); const char* nB = (has_next ? (const char*)g.Bt + (size_t)nxt.pn * tstepB : cB) + tail_;
;         for (int t = 0; t < nt; t += 2) {
;             if constexpr (Epi::MIDK) { if (t == (nt >> 1)) E.midk(acc, cur, wr, fr); }
;             const bool last = (t == nt - 2);
;             const char* a1 = cA + (size_t)(t + 1) * kstepA;
;             const char* a2 = last ? nA : cA + (size_t)(t + 2) * kstepA; const char* b2 = last ? nB : cB + (size_t)(t + 2) * kstep;
;             const char* a3 = a2 + kstepA; const char* b3 = b2 + kstep;
;             PG8_LDB(B0, 0, 0); PG8_LDB(B1, 0, 1); PG8_SCHED; PG8_LDA(At, 0, 0); PG8_STAGE(PG8_SA(1, 1), a1 + hstepA, voffA);
;             PG8_WAIT_V(8); PG8_WAIT_L(0); PG8_BAR; PG8_MMA(0, 0, At, B0); PG8_MMA(0, 1, At, B1); PG8_BAR; PG8_SCHED;
;     ...
; #pragma unroll
;         for (int a = 0; a < 2; ++a)
; #pragma unroll
;             for (int b = 0; b < 2; ++b)
; #pragma unroll
;                 for (int m = 0; m < 4; ++m)
; #pragma unroll
;                     for (int n = 0; n < 2; ++n) acc[a][b][m][n] = (f32x4){0.f, 0.f, 0.f, 0.f};
;         cur = nxt; cA = nA; cB = nB; ++ui;
.LBB0_900:
	s_ashr_i32 s21, s20, 31
	s_lshl_b64 s[22:23], s[20:21], 20
	s_add_u32 s2, s68, s22
	s_addc_u32 s19, s69, s23
	s_and_b64 s[22:23], s[0:1], exec
	s_cselect_b32 s2, s2, s28
	s_cselect_b32 s19, s19, s29
	s_add_u32 s22, s2, s24
	s_addc_u32 s23, s19, s25
	s_ashr_i32 s19, s18, 31
	s_lshl_b64 s[34:35], s[18:19], 20
	s_add_u32 s2, s78, s34
	s_addc_u32 s19, s79, s35
	s_and_b64 s[34:35], s[0:1], exec
	s_cselect_b32 s2, s2, s30
	s_cselect_b32 s19, s19, s31
	s_add_u32 s24, s2, s24
	s_addc_u32 s25, s19, s25
	s_add_u32 s28, s28, 0x80080
	s_addc_u32 s29, s29, 0
	s_add_u32 s19, s30, 0x100
	v_mov_b32_e32 v2, 0
	s_addc_u32 s21, s31, 0
	s_mov_b32 s49, -2
	v_mov_b32_e32 v3, v2
	v_mov_b32_e32 v4, v2
	v_mov_b32_e32 v5, v2
	v_mov_b32_e32 v6, v2
	v_mov_b32_e32 v7, v2
	v_mov_b32_e32 v8, v2
	v_mov_b32_e32 v9, v2
	v_mov_b32_e32 v18, v2
	v_mov_b32_e32 v19, v2
	v_mov_b32_e32 v20, v2
	v_mov_b32_e32 v21, v2
	v_mov_b32_e32 v22, v2
	v_mov_b32_e32 v23, v2
	v_mov_b32_e32 v24, v2
	v_mov_b32_e32 v25, v2
	v_mov_b32_e32 v34, v2
	v_mov_b32_e32 v35, v2
	v_mov_b32_e32 v36, v2
	v_mov_b32_e32 v37, v2
	v_mov_b32_e32 v38, v2
	v_mov_b32_e32 v39, v2
	v_mov_b32_e32 v40, v2
	v_mov_b32_e32 v41, v2
	v_mov_b32_e32 v50, v2
	v_mov_b32_e32 v51, v2
	v_mov_b32_e32 v52, v2
	v_mov_b32_e32 v53, v2
	v_mov_b32_e32 v54, v2
	v_mov_b32_e32 v55, v2
	v_mov_b32_e32 v56, v2
	v_mov_b32_e32 v57, v2
	v_mov_b32_e32 v10, v2
	v_mov_b32_e32 v11, v2
	v_mov_b32_e32 v12, v2
	v_mov_b32_e32 v13, v2
	v_mov_b32_e32 v14, v2
	v_mov_b32_e32 v15, v2
	v_mov_b32_e32 v16, v2
	v_mov_b32_e32 v17, v2
	v_mov_b32_e32 v26, v2
	v_mov_b32_e32 v27, v2
	v_mov_b32_e32 v28, v2
	v_mov_b32_e32 v29, v2
	v_mov_b32_e32 v30, v2
	v_mov_b32_e32 v31, v2
	v_mov_b32_e32 v32, v2
	v_mov_b32_e32 v33, v2
	v_mov_b32_e32 v42, v2
	v_mov_b32_e32 v43, v2
	v_mov_b32_e32 v44, v2
	v_mov_b32_e32 v45, v2
	v_mov_b32_e32 v46, v2
	v_mov_b32_e32 v47, v2
	v_mov_b32_e32 v48, v2
	v_mov_b32_e32 v49, v2
	v_mov_b32_e32 v58, v2
	v_mov_b32_e32 v59, v2
	v_mov_b32_e32 v60, v2
	v_mov_b32_e32 v61, v2
	v_mov_b32_e32 v62, v2
	v_mov_b32_e32 v63, v2
	v_mov_b32_e32 v64, v2
	v_mov_b32_e32 v65, v2
	v_mov_b32_e32 v66, v2
	v_mov_b32_e32 v67, v2
	v_mov_b32_e32 v68, v2
	v_mov_b32_e32 v69, v2
	v_mov_b32_e32 v70, v2
	v_mov_b32_e32 v71, v2
	v_mov_b32_e32 v72, v2
	v_mov_b32_e32 v73, v2
	v_mov_b32_e32 v82, v2
	v_mov_b32_e32 v83, v2
	v_mov_b32_e32 v84, v2
	v_mov_b32_e32 v85, v2
	v_mov_b32_e32 v86, v2
	v_mov_b32_e32 v87, v2
	v_mov_b32_e32 v88, v2
	v_mov_b32_e32 v89, v2
	v_mov_b32_e32 v98, v2
	v_mov_b32_e32 v99, v2
	v_mov_b32_e32 v100, v2
	v_mov_b32_e32 v101, v2
	v_mov_b32_e32 v102, v2
	v_mov_b32_e32 v103, v2
	v_mov_b32_e32 v104, v2
	v_mov_b32_e32 v105, v2
	v_mov_b32_e32 v114, v2
	v_mov_b32_e32 v115, v2
	v_mov_b32_e32 v116, v2
	v_mov_b32_e32 v117, v2
	v_mov_b32_e32 v118, v2
	v_mov_b32_e32 v119, v2
	v_mov_b32_e32 v120, v2
	v_mov_b32_e32 v121, v2
	v_mov_b32_e32 v74, v2
	v_mov_b32_e32 v75, v2
	v_mov_b32_e32 v76, v2
	v_mov_b32_e32 v77, v2
	v_mov_b32_e32 v78, v2
	v_mov_b32_e32 v79, v2
	v_mov_b32_e32 v80, v2
	v_mov_b32_e32 v81, v2
	v_mov_b32_e32 v90, v2
	v_mov_b32_e32 v91, v2
	v_mov_b32_e32 v92, v2
	v_mov_b32_e32 v93, v2
	v_mov_b32_e32 v94, v2
	v_mov_b32_e32 v95, v2
	v_mov_b32_e32 v96, v2
	v_mov_b32_e32 v97, v2
	v_mov_b32_e32 v106, v2
	v_mov_b32_e32 v107, v2
	v_mov_b32_e32 v108, v2
	v_mov_b32_e32 v109, v2
	v_mov_b32_e32 v110, v2
	v_mov_b32_e32 v111, v2
	v_mov_b32_e32 v112, v2
	v_mov_b32_e32 v113, v2
	v_mov_b32_e32 v122, v2
	v_mov_b32_e32 v123, v2
	v_mov_b32_e32 v124, v2
	v_mov_b32_e32 v125, v2
	v_mov_b32_e32 v126, v2
	v_mov_b32_e32 v127, v2
	v_mov_b32_e32 v128, v2
	v_mov_b32_e32 v129, v2
	s_and_b32 s2, s3, 0xfff
	s_mov_b32 s49, 0
	s_cmp_lt_u32 s3, 0x1000
	s_cbranch_scc0 .Lp8k_B_init
	s_mov_b64 s[50:51], s[24:25]
	s_cmp_eq_u32 s42, 1
	s_cbranch_scc1 .Lp8k_A_first
	s_add_u32 s28, s30, 0x100
	s_addc_u32 s29, s31, 0
	ds_read_b128 v[156:159], v153 offset:0
	ds_read_b128 v[160:163], v153 offset:1024
	s_branch .Lp8k_A_entry
.Lp8k_A_first:
	s_add_u32 s28, s30, 0x80
	s_addc_u32 s29, s31, 0
.Lp8k_A_loop:
	ds_read_b128 v[190:193], v155 offset:0
	ds_read_b128 v[194:197], v155 offset:1024
	ds_read_b128 v[198:201], v155 offset:2048
	s_add_i32 m0, s2, 0x18000
	s_nop 0
	global_load_lds_dwordx4 v134, s[28:29]
	ds_read_b128 v[202:205], v155 offset:3072
	ds_read_b128 v[206:209], v155 offset:4096
	ds_read_b128 v[210:213], v155 offset:5120
	s_add_i32 m0, s2, 0x1a000
	s_nop 0
	global_load_lds_dwordx4 v130, s[28:29]
	ds_read_b128 v[214:217], v155 offset:6144
	ds_read_b128 v[218:221], v155 offset:7168
	ds_read_b128 v[156:159], v153 offset:0
	s_add_u32 s30, s28, 0x20000
	s_addc_u32 s31, s29, 0
	s_add_i32 m0, s2, 0x19000
	s_nop 0
	global_load_lds_dwordx4 v134, s[30:31]
	ds_read_b128 v[160:163], v153 offset:1024
	ds_read_b128 v[164:167], v153 offset:2048
	ds_read_b128 v[168:171], v153 offset:3072
	s_add_i32 m0, s2, 0x1b000
	s_nop 0
	global_load_lds_dwordx4 v130, s[30:31]
	ds_read_b128 v[174:177], v153 offset:16384
	ds_read_b128 v[178:181], v153 offset:17408
	ds_read_b128 v[182:185], v153 offset:18432
	s_add_u32 s30, s28, 0x80000
	s_addc_u32 s31, s29, 0
	s_add_i32 m0, s2, 0x1c000
	s_nop 0
	global_load_lds_dwordx4 v134, s[30:31]
	ds_read_b128 v[186:189], v153 offset:19456
	ds_read_b128 v[222:225], v155 offset:16384
	ds_read_b128 v[226:229], v155 offset:17408
	s_add_i32 m0, s2, 0x1e000
	s_nop 0
	global_load_lds_dwordx4 v130, s[30:31]
	ds_read_b128 v[230:233], v155 offset:18432
	ds_read_b128 v[234:237], v155 offset:19456
	ds_read_b128 v[238:241], v155 offset:20480
	s_add_u32 s30, s28, 0xa0000
	s_addc_u32 s31, s29, 0
	s_add_i32 m0, s2, 0x1d000
	s_nop 0
	global_load_lds_dwordx4 v134, s[30:31]
	ds_read_b128 v[242:245], v155 offset:21504
	ds_read_b128 v[246:249], v155 offset:22528
	ds_read_b128 v[250:253], v155 offset:23552
	s_add_i32 m0, s2, 0x1f000
	s_nop 0
	global_load_lds_dwordx4 v130, s[30:31]
	s_add_u32 s28, s28, 0x80
	s_addc_u32 s29, s29, 0
; #define PG8_STAGE(bufoff, gbase, voff) do { _Pragma("unroll") for (int _i = 0; _i < 2; ++_i) \
;         __builtin_amdgcn_global_load_lds((const unsigned*)((const char*)(gbase) + (voff)[_i]), (PG8_LAS unsigned*)(lds + (bufoff) + ldsw + _i * 8192), 16, 0, 0); } while (0)
; #define PG8_LDA(dst, b, h) do { _Pragma("unroll") for (int m = 0; m < 4; ++m) _Pragma("unroll") for (int k = 0; k < 2; ++k) dst[m][k] = *(const PG8_LAS bf16x8*)(lds + PG8_SA(b, h) + aoff + m * 2048 + k * 1024); } while (0)
; #define PG8_LDB(dst, b, h) do { _Pragma("unroll") for (int n = 0; n < 2; ++n) _Pragma("unroll") for (int k = 0; k < 2; ++k) dst[n][k] = *(const PG8_LAS bf16x8*)(lds + PG8_SB(b, h) + boff + n * 2048 + k * 1024); } while (0)
; #define PG8_MMA(ai, bj, At, Bt) do { __builtin_amdgcn_s_setprio(1); _Pragma("unroll") for (int m = 0; m < 4; ++m) _Pragma("unroll") for (int n = 0; n < 2; ++n) _Pragma("unroll") for (int k = 0; k < 2; ++k) \
;         acc[ai][bj][m][n] = __builtin_amdgcn_mfma_f32_16x16x32_bf16(Bt[n][k], At[m][k], acc[ai][bj][m][n], 0, 0, 0); __builtin_amdgcn_s_setprio(0); } while (0)
; #define PG8_WAIT_V(n) asm volatile("s_waitcnt vmcnt(" #n ")" ::: "memory")
; template <class Epi, class Sched, bool ALIGN_EPI>
; __device__ __forceinline__ void gemm_phase(PG8_LAS unsigned char* lds, const Gemm g, const Sched& S, const Epi& E) {
;     ...
;             PG8_LDB(B0, 0, 0); PG8_LDB(B1, 0, 1); PG8_SCHED; PG8_LDA(At, 0, 0); PG8_STAGE(PG8_SA(1, 1), a1 + hstepA, voffA);
;             PG8_WAIT_V(8); PG8_WAIT_L(0); PG8_BAR; PG8_MMA(0, 0, At, B0); PG8_MMA(0, 1, At, B1); PG8_BAR; PG8_SCHED;
;             PG8_LDA(At, 0, 1); PG8_STAGE(PG8_SB(0, 0), b2, voffB); PG8_STAGE(PG8_SB(0, 1), b2 + hstepB, voffB); PG8_STAGE(PG8_SA(0, 0), a2, voffA);
;             PG8_WAIT_V(8); PG8_WAIT_L(0); PG8_BAR; PG8_MMA(1, 0, At, B0); PG8_MMA(1, 1, At, B1); PG8_BAR; PG8_SCHED;
;             PG8_LDB(B0, 1, 0); PG8_LDB(B1, 1, 1); PG8_SCHED; PG8_LDA(At, 1, 0); PG8_STAGE(PG8_SA(0, 1), a2 + hstepA, voffA);
;             PG8_WAIT_V(8); PG8_WAIT_L(0); PG8_BAR; PG8_MMA(0, 0, At, B0); PG8_MMA(0, 1, At, B1); PG8_BAR; PG8_SCHED;
;             PG8_LDA(At, 1, 1); PG8_STAGE(PG8_SB(1, 0), b3, voffB); PG8_STAGE(PG8_SB(1, 1), b3 + hstepB, voffB); PG8_STAGE(PG8_SA(1, 0), a3, voffA);
;             PG8_WAIT_V(8); PG8_WAIT_L(0); PG8_BAR; PG8_MMA(1, 0, At, B0); PG8_MMA(1, 1, At, B1); PG8_BAR; PG8_SCHED;
.Lp8k_A_entry:
	s_waitcnt vmcnt(8) lgkmcnt(0)
	s_barrier
	s_setprio 1
	v_mfma_f32_16x16x32_bf16 v[126:129], v[156:159], v[190:193], v[126:129]
	v_mfma_f32_16x16x32_bf16 v[126:129], v[160:163], v[194:197], v[126:129]
	v_mfma_f32_16x16x32_bf16 v[122:125], v[168:171], v[194:197], v[122:125]
	v_mfma_f32_16x16x32_bf16 v[122:125], v[164:167], v[190:193], v[122:125]
	v_mfma_f32_16x16x32_bf16 v[118:121], v[174:177], v[190:193], v[118:121]
	v_mfma_f32_16x16x32_bf16 v[118:121], v[178:181], v[194:197], v[118:121]
	v_mfma_f32_16x16x32_bf16 v[114:117], v[186:189], v[194:197], v[114:117]
	v_mfma_f32_16x16x32_bf16 v[114:117], v[182:185], v[190:193], v[114:117]
	v_mfma_f32_16x16x32_bf16 v[98:101], v[182:185], v[198:201], v[98:101]
	v_mfma_f32_16x16x32_bf16 v[98:101], v[186:189], v[202:205], v[98:101]
	v_mfma_f32_16x16x32_bf16 v[102:105], v[178:181], v[202:205], v[102:105]
	v_mfma_f32_16x16x32_bf16 v[102:105], v[174:177], v[198:201], v[102:105]
	v_mfma_f32_16x16x32_bf16 v[106:109], v[164:167], v[198:201], v[106:109]
	v_mfma_f32_16x16x32_bf16 v[106:109], v[168:171], v[202:205], v[106:109]
	v_mfma_f32_16x16x32_bf16 v[110:113], v[160:163], v[202:205], v[110:113]
	v_mfma_f32_16x16x32_bf16 v[110:113], v[156:159], v[198:201], v[110:113]
	v_mfma_f32_16x16x32_bf16 v[94:97], v[156:159], v[206:209], v[94:97]
	v_mfma_f32_16x16x32_bf16 v[94:97], v[160:163], v[210:213], v[94:97]
	v_mfma_f32_16x16x32_bf16 v[90:93], v[168:171], v[210:213], v[90:93]
	v_mfma_f32_16x16x32_bf16 v[90:93], v[164:167], v[206:209], v[90:93]
	v_mfma_f32_16x16x32_bf16 v[86:89], v[174:177], v[206:209], v[86:89]
	v_mfma_f32_16x16x32_bf16 v[86:89], v[178:181], v[210:213], v[86:89]
	v_mfma_f32_16x16x32_bf16 v[82:85], v[186:189], v[210:213], v[82:85]
	v_mfma_f32_16x16x32_bf16 v[82:85], v[182:185], v[206:209], v[82:85]
	v_mfma_f32_16x16x32_bf16 v[66:69], v[182:185], v[214:217], v[66:69]
	v_mfma_f32_16x16x32_bf16 v[66:69], v[186:189], v[218:221], v[66:69]
	v_mfma_f32_16x16x32_bf16 v[70:73], v[178:181], v[218:221], v[70:73]
	v_mfma_f32_16x16x32_bf16 v[70:73], v[174:177], v[214:217], v[70:73]
	v_mfma_f32_16x16x32_bf16 v[74:77], v[164:167], v[214:217], v[74:77]
	v_mfma_f32_16x16x32_bf16 v[74:77], v[168:171], v[218:221], v[74:77]
	v_mfma_f32_16x16x32_bf16 v[78:81], v[160:163], v[218:221], v[78:81]
	v_mfma_f32_16x16x32_bf16 v[78:81], v[156:159], v[214:217], v[78:81]
	v_mfma_f32_16x16x32_bf16 v[62:65], v[156:159], v[222:225], v[62:65]
	v_mfma_f32_16x16x32_bf16 v[62:65], v[160:163], v[226:229], v[62:65]
	v_mfma_f32_16x16x32_bf16 v[58:61], v[168:171], v[226:229], v[58:61]
	v_mfma_f32_16x16x32_bf16 v[58:61], v[164:167], v[222:225], v[58:61]
	v_mfma_f32_16x16x32_bf16 v[54:57], v[174:177], v[222:225], v[54:57]
	v_mfma_f32_16x16x32_bf16 v[54:57], v[178:181], v[226:229], v[54:57]
	v_mfma_f32_16x16x32_bf16 v[50:53], v[186:189], v[226:229], v[50:53]
	v_mfma_f32_16x16x32_bf16 v[50:53], v[182:185], v[222:225], v[50:53]
	v_mfma_f32_16x16x32_bf16 v[34:37], v[182:185], v[230:233], v[34:37]
	v_mfma_f32_16x16x32_bf16 v[34:37], v[186:189], v[234:237], v[34:37]
	v_mfma_f32_16x16x32_bf16 v[38:41], v[178:181], v[234:237], v[38:41]
	v_mfma_f32_16x16x32_bf16 v[38:41], v[174:177], v[230:233], v[38:41]
	v_mfma_f32_16x16x32_bf16 v[42:45], v[164:167], v[230:233], v[42:45]
	v_mfma_f32_16x16x32_bf16 v[42:45], v[168:171], v[234:237], v[42:45]
	v_mfma_f32_16x16x32_bf16 v[46:49], v[160:163], v[234:237], v[46:49]
	v_mfma_f32_16x16x32_bf16 v[46:49], v[156:159], v[230:233], v[46:49]
	v_mfma_f32_16x16x32_bf16 v[30:33], v[156:159], v[238:241], v[30:33]
	v_mfma_f32_16x16x32_bf16 v[30:33], v[160:163], v[242:245], v[30:33]
	v_mfma_f32_16x16x32_bf16 v[26:29], v[168:171], v[242:245], v[26:29]
	v_mfma_f32_16x16x32_bf16 v[26:29], v[164:167], v[238:241], v[26:29]
	v_mfma_f32_16x16x32_bf16 v[22:25], v[174:177], v[238:241], v[22:25]
	v_mfma_f32_16x16x32_bf16 v[22:25], v[178:181], v[242:245], v[22:25]
	v_mfma_f32_16x16x32_bf16 v[18:21], v[186:189], v[242:245], v[18:21]
	v_mfma_f32_16x16x32_bf16 v[18:21], v[182:185], v[238:241], v[18:21]
	v_mfma_f32_16x16x32_bf16 v[2:5], v[182:185], v[246:249], v[2:5]
	v_mfma_f32_16x16x32_bf16 v[2:5], v[186:189], v[250:253], v[2:5]
	v_mfma_f32_16x16x32_bf16 v[6:9], v[178:181], v[250:253], v[6:9]
	v_mfma_f32_16x16x32_bf16 v[6:9], v[174:177], v[246:249], v[6:9]
	v_mfma_f32_16x16x32_bf16 v[10:13], v[164:167], v[246:249], v[10:13]
	v_mfma_f32_16x16x32_bf16 v[10:13], v[168:171], v[250:253], v[10:13]
	v_mfma_f32_16x16x32_bf16 v[14:17], v[160:163], v[250:253], v[14:17]
	v_mfma_f32_16x16x32_bf16 v[14:17], v[156:159], v[246:249], v[14:17]
	s_setprio 0
	s_waitcnt vmcnt(0)
	s_barrier
	ds_read_b128 v[190:193], v155 offset:32768
	ds_read_b128 v[194:197], v155 offset:33792
	ds_read_b128 v[198:201], v155 offset:34816
	s_cmp_eq_u32 s49, 15
	s_cselect_b32 s28, s50, s28
	s_cselect_b32 s29, s51, s29
	s_add_i32 m0, s2, 0x10000
	s_nop 0
	global_load_lds_dwordx4 v134, s[28:29]
	ds_read_b128 v[202:205], v155 offset:35840
	ds_read_b128 v[206:209], v155 offset:36864
	ds_read_b128 v[210:213], v155 offset:37888
	s_add_i32 m0, s2, 0x12000
	s_nop 0
	global_load_lds_dwordx4 v130, s[28:29]
	ds_read_b128 v[214:217], v155 offset:38912
	ds_read_b128 v[218:221], v155 offset:39936
	ds_read_b128 v[156:159], v153 offset:32768
	s_add_u32 s30, s28, 0x20000
	s_addc_u32 s31, s29, 0
	s_add_i32 m0, s2, 0x11000
	s_nop 0
	global_load_lds_dwordx4 v134, s[30:31]
	ds_read_b128 v[160:163], v153 offset:33792
	ds_read_b128 v[164:167], v153 offset:34816
	ds_read_b128 v[168:171], v153 offset:35840
	s_add_i32 m0, s2, 0x13000
	s_nop 0
	global_load_lds_dwordx4 v130, s[30:31]
	ds_read_b128 v[174:177], v153 offset:49152
	ds_read_b128 v[178:181], v153 offset:50176
	ds_read_b128 v[182:185], v153 offset:51200
	s_add_u32 s30, s28, 0x80000
	s_addc_u32 s31, s29, 0
	s_add_i32 m0, s2, 0x14000
	s_nop 0
	global_load_lds_dwordx4 v134, s[30:31]
	ds_read_b128 v[186:189], v153 offset:52224
	ds_read_b128 v[222:225], v155 offset:49152
	ds_read_b128 v[226:229], v155 offset:50176
	s_add_i32 m0, s2, 0x16000
	s_nop 0
	global_load_lds_dwordx4 v130, s[30:31]
	ds_read_b128 v[230:233], v155 offset:51200
	ds_read_b128 v[234:237], v155 offset:52224
	ds_read_b128 v[238:241], v155 offset:53248
	s_add_u32 s30, s28, 0xa0000
	s_addc_u32 s31, s29, 0
	s_add_i32 m0, s2, 0x15000
	s_nop 0
	global_load_lds_dwordx4 v134, s[30:31]
	ds_read_b128 v[242:245], v155 offset:54272
	ds_read_b128 v[246:249], v155 offset:55296
	ds_read_b128 v[250:253], v155 offset:56320
	s_add_i32 m0, s2, 0x17000
	s_nop 0
	global_load_lds_dwordx4 v130, s[30:31]
	s_add_u32 s28, s28, 0x80
	s_addc_u32 s29, s29, 0
	s_waitcnt vmcnt(8) lgkmcnt(0)
	s_barrier
; #define PG8_STAGE(bufoff, gbase, voff) do { _Pragma("unroll") for (int _i = 0; _i < 2; ++_i) \
;         __builtin_amdgcn_global_load_lds((const unsigned*)((const char*)(gbase) + (voff)[_i]), (PG8_LAS unsigned*)(lds + (bufoff) + ldsw + _i * 8192), 16, 0, 0); } while (0)
; #define PG8_LDA(dst, b, h) do { _Pragma("unroll") for (int m = 0; m < 4; ++m) _Pragma("unroll") for (int k = 0; k < 2; ++k) dst[m][k] = *(const PG8_LAS bf16x8*)(lds + PG8_SA(b, h) + aoff + m * 2048 + k * 1024); } while (0)
; #define PG8_LDB(dst, b, h) do { _Pragma("unroll") for (int n = 0; n < 2; ++n) _Pragma("unroll") for (int k = 0; k < 2; ++k) dst[n][k] = *(const PG8_LAS bf16x8*)(lds + PG8_SB(b, h) + boff + n * 2048 + k * 1024); } while (0)
; #define PG8_MMA(ai, bj, At, Bt) do { __builtin_amdgcn_s_setprio(1); _Pragma("unroll") for (int m = 0; m < 4; ++m) _Pragma("unroll") for (int n = 0; n < 2; ++n) _Pragma("unroll") for (int k = 0; k < 2; ++k) \
;         acc[ai][bj][m][n] = __builtin_amdgcn_mfma_f32_16x16x32_bf16(Bt[n][k], At[m][k], acc[ai][bj][m][n], 0, 0, 0); __builtin_amdgcn_s_setprio(0); } while (0)
; template <class Epi, class Sched, bool ALIGN_EPI>
; __device__ __forceinline__ void gemm_phase(PG8_LAS unsigned char* lds, const Gemm g, const Sched& S, const Epi& E) {
;     ...
;             PG8_LDB(B0, 0, 0); PG8_LDB(B1, 0, 1); PG8_SCHED; PG8_LDA(At, 0, 0); PG8_STAGE(PG8_SA(1, 1), a1 + hstepA, voffA);
;             PG8_WAIT_V(8); PG8_WAIT_L(0); PG8_BAR; PG8_MMA(0, 0, At, B0); PG8_MMA(0, 1, At, B1); PG8_BAR; PG8_SCHED;
;             PG8_LDA(At, 0, 1); PG8_STAGE(PG8_SB(0, 0), b2, voffB); PG8_STAGE(PG8_SB(0, 1), b2 + hstepB, voffB); PG8_STAGE(PG8_SA(0, 0), a2, voffA);
;             PG8_WAIT_V(8); PG8_WAIT_L(0); PG8_BAR; PG8_MMA(1, 0, At, B0); PG8_MMA(1, 1, At, B1); PG8_BAR; PG8_SCHED;
;             PG8_LDB(B0, 1, 0); PG8_LDB(B1, 1, 1); PG8_SCHED; PG8_LDA(At, 1, 0); PG8_STAGE(PG8_SA(0, 1), a2 + hstepA, voffA);
;             PG8_WAIT_V(8); PG8_WAIT_L(0); PG8_BAR; PG8_MMA(0, 0, At, B0); PG8_MMA(0, 1, At, B1); PG8_BAR; PG8_SCHED;
;             PG8_LDA(At, 1, 1); PG8_STAGE(PG8_SB(1, 0), b3, voffB); PG8_STAGE(PG8_SB(1, 1), b3 + hstepB, voffB); PG8_STAGE(PG8_SA(1, 0), a3, voffA);
;             PG8_WAIT_V(8); PG8_WAIT_L(0); PG8_BAR; PG8_MMA(1, 0, At, B0); PG8_MMA(1, 1, At, B1); PG8_BAR; PG8_SCHED;
;         }
;         if constexpr (ALIGN_EPI) { if (wr == 0) PG8_BAR; }
	s_setprio 1
	v_mfma_f32_16x16x32_bf16 v[126:129], v[156:159], v[190:193], v[126:129]
	v_mfma_f32_16x16x32_bf16 v[126:129], v[160:163], v[194:197], v[126:129]
	v_mfma_f32_16x16x32_bf16 v[122:125], v[168:171], v[194:197], v[122:125]
	v_mfma_f32_16x16x32_bf16 v[122:125], v[164:167], v[190:193], v[122:125]
	v_mfma_f32_16x16x32_bf16 v[118:121], v[174:177], v[190:193], v[118:121]
	v_mfma_f32_16x16x32_bf16 v[118:121], v[178:181], v[194:197], v[118:121]
	v_mfma_f32_16x16x32_bf16 v[114:117], v[186:189], v[194:197], v[114:117]
	v_mfma_f32_16x16x32_bf16 v[114:117], v[182:185], v[190:193], v[114:117]
	v_mfma_f32_16x16x32_bf16 v[98:101], v[182:185], v[198:201], v[98:101]
	v_mfma_f32_16x16x32_bf16 v[98:101], v[186:189], v[202:205], v[98:101]
	v_mfma_f32_16x16x32_bf16 v[102:105], v[178:181], v[202:205], v[102:105]
	v_mfma_f32_16x16x32_bf16 v[102:105], v[174:177], v[198:201], v[102:105]
	v_mfma_f32_16x16x32_bf16 v[106:109], v[164:167], v[198:201], v[106:109]
	v_mfma_f32_16x16x32_bf16 v[106:109], v[168:171], v[202:205], v[106:109]
	v_mfma_f32_16x16x32_bf16 v[110:113], v[160:163], v[202:205], v[110:113]
	v_mfma_f32_16x16x32_bf16 v[110:113], v[156:159], v[198:201], v[110:113]
	v_mfma_f32_16x16x32_bf16 v[94:97], v[156:159], v[206:209], v[94:97]
	v_mfma_f32_16x16x32_bf16 v[94:97], v[160:163], v[210:213], v[94:97]
	v_mfma_f32_16x16x32_bf16 v[90:93], v[168:171], v[210:213], v[90:93]
	v_mfma_f32_16x16x32_bf16 v[90:93], v[164:167], v[206:209], v[90:93]
	v_mfma_f32_16x16x32_bf16 v[86:89], v[174:177], v[206:209], v[86:89]
	v_mfma_f32_16x16x32_bf16 v[86:89], v[178:181], v[210:213], v[86:89]
	v_mfma_f32_16x16x32_bf16 v[82:85], v[186:189], v[210:213], v[82:85]
	v_mfma_f32_16x16x32_bf16 v[82:85], v[182:185], v[206:209], v[82:85]
	v_mfma_f32_16x16x32_bf16 v[66:69], v[182:185], v[214:217], v[66:69]
	v_mfma_f32_16x16x32_bf16 v[66:69], v[186:189], v[218:221], v[66:69]
	v_mfma_f32_16x16x32_bf16 v[70:73], v[178:181], v[218:221], v[70:73]
	v_mfma_f32_16x16x32_bf16 v[70:73], v[174:177], v[214:217], v[70:73]
	v_mfma_f32_16x16x32_bf16 v[74:77], v[164:167], v[214:217], v[74:77]
	v_mfma_f32_16x16x32_bf16 v[74:77], v[168:171], v[218:221], v[74:77]
	v_mfma_f32_16x16x32_bf16 v[78:81], v[160:163], v[218:221], v[78:81]
	v_mfma_f32_16x16x32_bf16 v[78:81], v[156:159], v[214:217], v[78:81]
	v_mfma_f32_16x16x32_bf16 v[62:65], v[156:159], v[222:225], v[62:65]
	v_mfma_f32_16x16x32_bf16 v[62:65], v[160:163], v[226:229], v[62:65]
	v_mfma_f32_16x16x32_bf16 v[58:61], v[168:171], v[226:229], v[58:61]
	v_mfma_f32_16x16x32_bf16 v[58:61], v[164:167], v[222:225], v[58:61]
	v_mfma_f32_16x16x32_bf16 v[54:57], v[174:177], v[222:225], v[54:57]
	v_mfma_f32_16x16x32_bf16 v[54:57], v[178:181], v[226:229], v[54:57]
	v_mfma_f32_16x16x32_bf16 v[50:53], v[186:189], v[226:229], v[50:53]
	v_mfma_f32_16x16x32_bf16 v[50:53], v[182:185], v[222:225], v[50:53]
	v_mfma_f32_16x16x32_bf16 v[34:37], v[182:185], v[230:233], v[34:37]
	v_mfma_f32_16x16x32_bf16 v[34:37], v[186:189], v[234:237], v[34:37]
	v_mfma_f32_16x16x32_bf16 v[38:41], v[178:181], v[234:237], v[38:41]
	v_mfma_f32_16x16x32_bf16 v[38:41], v[174:177], v[230:233], v[38:41]
	v_mfma_f32_16x16x32_bf16 v[42:45], v[164:167], v[230:233], v[42:45]
	v_mfma_f32_16x16x32_bf16 v[42:45], v[168:171], v[234:237], v[42:45]
	v_mfma_f32_16x16x32_bf16 v[46:49], v[160:163], v[234:237], v[46:49]
	v_mfma_f32_16x16x32_bf16 v[46:49], v[156:159], v[230:233], v[46:49]
	v_mfma_f32_16x16x32_bf16 v[30:33], v[156:159], v[238:241], v[30:33]
	v_mfma_f32_16x16x32_bf16 v[30:33], v[160:163], v[242:245], v[30:33]
	v_mfma_f32_16x16x32_bf16 v[26:29], v[168:171], v[242:245], v[26:29]
	v_mfma_f32_16x16x32_bf16 v[26:29], v[164:167], v[238:241], v[26:29]
	v_mfma_f32_16x16x32_bf16 v[22:25], v[174:177], v[238:241], v[22:25]
	v_mfma_f32_16x16x32_bf16 v[22:25], v[178:181], v[242:245], v[22:25]
	v_mfma_f32_16x16x32_bf16 v[18:21], v[186:189], v[242:245], v[18:21]
	v_mfma_f32_16x16x32_bf16 v[18:21], v[182:185], v[238:241], v[18:21]
	v_mfma_f32_16x16x32_bf16 v[2:5], v[182:185], v[246:249], v[2:5]
	v_mfma_f32_16x16x32_bf16 v[2:5], v[186:189], v[250:253], v[2:5]
	v_mfma_f32_16x16x32_bf16 v[6:9], v[178:181], v[250:253], v[6:9]
	v_mfma_f32_16x16x32_bf16 v[6:9], v[174:177], v[246:249], v[6:9]
	v_mfma_f32_16x16x32_bf16 v[10:13], v[164:167], v[246:249], v[10:13]
	v_mfma_f32_16x16x32_bf16 v[10:13], v[168:171], v[250:253], v[10:13]
	v_mfma_f32_16x16x32_bf16 v[14:17], v[160:163], v[250:253], v[14:17]
	v_mfma_f32_16x16x32_bf16 v[14:17], v[156:159], v[246:249], v[14:17]
	s_setprio 0
	s_waitcnt vmcnt(0)
	s_barrier
	s_add_i32 s49, s49, 1
	s_cmp_lt_u32 s49, 16
	s_cbranch_scc1 .Lp8k_A_loop
	ds_read_b128 v[190:193], v155 offset:0
	ds_read_b128 v[194:197], v155 offset:1024
	ds_read_b128 v[198:201], v155 offset:2048
	s_add_i32 m0, s2, 0x18000
	s_nop 0
	global_load_lds_dwordx4 v134, s[28:29]
	ds_read_b128 v[202:205], v155 offset:3072
	ds_read_b128 v[206:209], v155 offset:4096
	ds_read_b128 v[210:213], v155 offset:5120
	s_add_i32 m0, s2, 0x1a000
	s_nop 0
	global_load_lds_dwordx4 v130, s[28:29]
	ds_read_b128 v[214:217], v155 offset:6144
	ds_read_b128 v[218:221], v155 offset:7168
	ds_read_b128 v[164:167], v153 offset:2048
	s_add_u32 s30, s28, 0x20000
	s_addc_u32 s31, s29, 0
	s_add_i32 m0, s2, 0x19000
	s_nop 0
	global_load_lds_dwordx4 v134, s[30:31]
	ds_read_b128 v[168:171], v153 offset:3072
	ds_read_b128 v[174:177], v153 offset:16384
	ds_read_b128 v[178:181], v153 offset:17408
	s_add_i32 m0, s2, 0x1b000
	s_nop 0
	global_load_lds_dwordx4 v130, s[30:31]
	ds_read_b128 v[182:185], v153 offset:18432
	ds_read_b128 v[186:189], v153 offset:19456
	ds_read_b128 v[222:225], v155 offset:16384
	s_add_u32 s30, s28, 0x80000
	s_addc_u32 s31, s29, 0
	s_add_i32 m0, s2, 0x1c000
	s_nop 0
	global_load_lds_dwordx4 v134, s[30:31]
	ds_read_b128 v[226:229], v155 offset:17408
	ds_read_b128 v[230:233], v155 offset:18432
	ds_read_b128 v[234:237], v155 offset:19456
	s_add_i32 m0, s2, 0x1e000
	s_nop 0
	global_load_lds_dwordx4 v130, s[30:31]
	ds_read_b128 v[238:241], v155 offset:20480
	ds_read_b128 v[242:245], v155 offset:21504
	ds_read_b128 v[246:249], v155 offset:22528
	s_add_u32 s30, s28, 0xa0000
	s_addc_u32 s31, s29, 0
	s_add_i32 m0, s2, 0x1d000
	s_nop 0
	global_load_lds_dwordx4 v134, s[30:31]
	ds_read_b128 v[250:253], v155 offset:23552
	s_add_i32 m0, s2, 0x1f000
	s_nop 0
	global_load_lds_dwordx4 v130, s[30:31]
	s_add_u32 s28, s28, 0x80
	s_addc_u32 s29, s29, 0
	s_branch .Lp8k_done
; #define PG8_STAGE(bufoff, gbase, voff) do { _Pragma("unroll") for (int _i = 0; _i < 2; ++_i) \
;         __builtin_amdgcn_global_load_lds((const unsigned*)((const char*)(gbase) + (voff)[_i]), (PG8_LAS unsigned*)(lds + (bufoff) + ldsw + _i * 8192), 16, 0, 0); } while (0)
; #define PG8_LDA(dst, b, h) do { _Pragma("unroll") for (int m = 0; m < 4; ++m) _Pragma("unroll") for (int k = 0; k < 2; ++k) dst[m][k] = *(const PG8_LAS bf16x8*)(lds + PG8_SA(b, h) + aoff + m * 2048 + k * 1024); } while (0)
; #define PG8_LDB(dst, b, h) do { _Pragma("unroll") for (int n = 0; n < 2; ++n) _Pragma("unroll") for (int k = 0; k < 2; ++k) dst[n][k] = *(const PG8_LAS bf16x8*)(lds + PG8_SB(b, h) + boff + n * 2048 + k * 1024); } while (0)
; #define PG8_MMA(ai, bj, At, Bt) do { __builtin_amdgcn_s_setprio(1); _Pragma("unroll") for (int m = 0; m < 4; ++m) _Pragma("unroll") for (int n = 0; n < 2; ++n) _Pragma("unroll") for (int k = 0; k < 2; ++k) \
;         acc[ai][bj][m][n] = __builtin_amdgcn_mfma_f32_16x16x32_bf16(Bt[n][k], At[m][k], acc[ai][bj][m][n], 0, 0, 0); __builtin_amdgcn_s_setprio(0); } while (0)
; #define PG8_WAIT_V(n) asm volatile("s_waitcnt vmcnt(" #n ")" ::: "memory")
; #define PG8_WAIT_L(n) asm volatile("s_waitcnt lgkmcnt(" #n ")" ::: "memory")
; #define PG8_BAR __builtin_amdgcn_s_barrier()
; #define PG8_SCHED __builtin_amdgcn_sched_barrier(0)
; template <class Epi, class Sched, bool ALIGN_EPI>
; __device__ __forceinline__ void gemm_phase(PG8_LAS unsigned char* lds, const Gemm g, const Sched& S, const Epi& E) {
;     ...
;             const char* a2 = last ? nA : cA + (size_t)(t + 2) * kstepA; const char* b2 = last ? nB : cB + (size_t)(t + 2) * kstep;
;             const char* a3 = a2 + kstepA; const char* b3 = b2 + kstep;
;             PG8_LDB(B0, 0, 0); PG8_LDB(B1, 0, 1); PG8_SCHED; PG8_LDA(At, 0, 0); PG8_STAGE(PG8_SA(1, 1), a1 + hstepA, voffA);
;             PG8_WAIT_V(8); PG8_WAIT_L(0); PG8_BAR; PG8_MMA(0, 0, At, B0); PG8_MMA(0, 1, At, B1); PG8_BAR; PG8_SCHED;
;             PG8_LDA(At, 0, 1); PG8_STAGE(PG8_SB(0, 0), b2, voffB); PG8_STAGE(PG8_SB(0, 1), b2 + hstepB, voffB); PG8_STAGE(PG8_SA(0, 0), a2, voffA);
;             PG8_WAIT_V(8); PG8_WAIT_L(0); PG8_BAR; PG8_MMA(1, 0, At, B0); PG8_MMA(1, 1, At, B1); PG8_BAR; PG8_SCHED;
.Lp8k_B_init:
	s_sub_u32 s28, s28, 0xa0000
	s_subb_u32 s29, s29, 0
	s_sub_u32 s50, s22, 0x20000
	s_subb_u32 s51, s23, 0
	s_cmp_eq_u32 s42, 1
	s_cbranch_scc1 .Lp8k_B_nobar
	s_barrier
.Lp8k_B_nobar:
.Lp8k_B_loop:
	ds_read_b128 v[190:193], v155 offset:0
	ds_read_b128 v[194:197], v155 offset:1024
	ds_read_b128 v[198:201], v155 offset:2048
	s_add_i32 m0, s2, 0xa000
	s_nop 0
	global_load_lds_dwordx4 v132, s[28:29]
	ds_read_b128 v[202:205], v155 offset:3072
	ds_read_b128 v[206:209], v155 offset:4096
	ds_read_b128 v[210:213], v155 offset:5120
	s_add_u32 s30, s28, 0x20000
	s_addc_u32 s31, s29, 0
	s_add_i32 m0, s2, 0xb000
	s_nop 0
	global_load_lds_dwordx4 v132, s[30:31]
	ds_read_b128 v[214:217], v155 offset:6144
	ds_read_b128 v[218:221], v155 offset:7168
	ds_read_b128 v[156:159], v153 offset:0
	s_add_u32 s30, s28, 0x80000
	s_addc_u32 s31, s29, 0
	s_add_i32 m0, s2, 0xe000
	s_nop 0
	global_load_lds_dwordx4 v132, s[30:31]
	ds_read_b128 v[160:163], v153 offset:1024
	ds_read_b128 v[164:167], v153 offset:2048
	ds_read_b128 v[168:171], v153 offset:3072
	s_add_u32 s30, s28, 0xa0000
	s_addc_u32 s31, s29, 0
	s_add_i32 m0, s2, 0xf000
	s_nop 0
	global_load_lds_dwordx4 v132, s[30:31]
	ds_read_b128 v[174:177], v153 offset:16384
	ds_read_b128 v[178:181], v153 offset:17408
	ds_read_b128 v[182:185], v153 offset:18432
	s_add_u32 s34, s28, 0x80
	s_addc_u32 s35, s29, 0
	s_cmp_eq_u32 s49, 15
	s_cselect_b32 s34, s50, s34
	s_cselect_b32 s35, s51, s35
	s_add_i32 m0, s2, 0x0
	s_nop 0
	global_load_lds_dwordx4 v136, s[34:35]
	ds_read_b128 v[186:189], v153 offset:19456
	ds_read_b128 v[222:225], v155 offset:16384
	ds_read_b128 v[226:229], v155 offset:17408
	s_add_u32 s30, s34, 0x20000
	s_addc_u32 s31, s35, 0
	s_add_i32 m0, s2, 0x1000
	s_nop 0
	global_load_lds_dwordx4 v136, s[30:31]
	ds_read_b128 v[230:233], v155 offset:18432
	ds_read_b128 v[234:237], v155 offset:19456
	ds_read_b128 v[238:241], v155 offset:20480
	s_add_u32 s30, s34, 0x80000
	s_addc_u32 s31, s35, 0
	s_add_i32 m0, s2, 0x4000
	s_nop 0
	global_load_lds_dwordx4 v136, s[30:31]
	ds_read_b128 v[242:245], v155 offset:21504
	ds_read_b128 v[246:249], v155 offset:22528
	ds_read_b128 v[250:253], v155 offset:23552
	s_add_u32 s30, s34, 0xa0000
	s_addc_u32 s31, s35, 0
	s_add_i32 m0, s2, 0x5000
	s_nop 0
	global_load_lds_dwordx4 v136, s[30:31]
	s_add_u32 s28, s28, 0x80
	s_addc_u32 s29, s29, 0
	s_waitcnt vmcnt(8) lgkmcnt(0)
	s_barrier
	s_setprio 1
	v_mfma_f32_16x16x32_bf16 v[126:129], v[156:159], v[190:193], v[126:129]
	v_mfma_f32_16x16x32_bf16 v[126:129], v[160:163], v[194:197], v[126:129]
	v_mfma_f32_16x16x32_bf16 v[122:125], v[168:171], v[194:197], v[122:125]
	v_mfma_f32_16x16x32_bf16 v[122:125], v[164:167], v[190:193], v[122:125]
	v_mfma_f32_16x16x32_bf16 v[118:121], v[174:177], v[190:193], v[118:121]
	v_mfma_f32_16x16x32_bf16 v[118:121], v[178:181], v[194:197], v[118:121]
	v_mfma_f32_16x16x32_bf16 v[114:117], v[186:189], v[194:197], v[114:117]
	v_mfma_f32_16x16x32_bf16 v[114:117], v[182:185], v[190:193], v[114:117]
	v_mfma_f32_16x16x32_bf16 v[98:101], v[182:185], v[198:201], v[98:101]
	v_mfma_f32_16x16x32_bf16 v[98:101], v[186:189], v[202:205], v[98:101]
	v_mfma_f32_16x16x32_bf16 v[102:105], v[178:181], v[202:205], v[102:105]
	v_mfma_f32_16x16x32_bf16 v[102:105], v[174:177], v[198:201], v[102:105]
	v_mfma_f32_16x16x32_bf16 v[106:109], v[164:167], v[198:201], v[106:109]
	v_mfma_f32_16x16x32_bf16 v[106:109], v[168:171], v[202:205], v[106:109]
	v_mfma_f32_16x16x32_bf16 v[110:113], v[160:163], v[202:205], v[110:113]
	v_mfma_f32_16x16x32_bf16 v[110:113], v[156:159], v[198:201], v[110:113]
	v_mfma_f32_16x16x32_bf16 v[94:97], v[156:159], v[206:209], v[94:97]
	v_mfma_f32_16x16x32_bf16 v[94:97], v[160:163], v[210:213], v[94:97]
	v_mfma_f32_16x16x32_bf16 v[90:93], v[168:171], v[210:213], v[90:93]
	v_mfma_f32_16x16x32_bf16 v[90:93], v[164:167], v[206:209], v[90:93]
	v_mfma_f32_16x16x32_bf16 v[86:89], v[174:177], v[206:209], v[86:89]
	v_mfma_f32_16x16x32_bf16 v[86:89], v[178:181], v[210:213], v[86:89]
	v_mfma_f32_16x16x32_bf16 v[82:85], v[186:189], v[210:213], v[82:85]
	v_mfma_f32_16x16x32_bf16 v[82:85], v[182:185], v[206:209], v[82:85]
	v_mfma_f32_16x16x32_bf16 v[66:69], v[182:185], v[214:217], v[66:69]
	v_mfma_f32_16x16x32_bf16 v[66:69], v[186:189], v[218:221], v[66:69]
	v_mfma_f32_16x16x32_bf16 v[70:73], v[178:181], v[218:221], v[70:73]
	v_mfma_f32_16x16x32_bf16 v[70:73], v[174:177], v[214:217], v[70:73]
	v_mfma_f32_16x16x32_bf16 v[74:77], v[164:167], v[214:217], v[74:77]
	v_mfma_f32_16x16x32_bf16 v[74:77], v[168:171], v[218:221], v[74:77]
	v_mfma_f32_16x16x32_bf16 v[78:81], v[160:163], v[218:221], v[78:81]
	v_mfma_f32_16x16x32_bf16 v[78:81], v[156:159], v[214:217], v[78:81]
	v_mfma_f32_16x16x32_bf16 v[62:65], v[156:159], v[222:225], v[62:65]
	v_mfma_f32_16x16x32_bf16 v[62:65], v[160:163], v[226:229], v[62:65]
	v_mfma_f32_16x16x32_bf16 v[58:61], v[168:171], v[226:229], v[58:61]
	v_mfma_f32_16x16x32_bf16 v[58:61], v[164:167], v[222:225], v[58:61]
	v_mfma_f32_16x16x32_bf16 v[54:57], v[174:177], v[222:225], v[54:57]
	v_mfma_f32_16x16x32_bf16 v[54:57], v[178:181], v[226:229], v[54:57]
	v_mfma_f32_16x16x32_bf16 v[50:53], v[186:189], v[226:229], v[50:53]
	v_mfma_f32_16x16x32_bf16 v[50:53], v[182:185], v[222:225], v[50:53]
	v_mfma_f32_16x16x32_bf16 v[34:37], v[182:185], v[230:233], v[34:37]
	v_mfma_f32_16x16x32_bf16 v[34:37], v[186:189], v[234:237], v[34:37]
	v_mfma_f32_16x16x32_bf16 v[38:41], v[178:181], v[234:237], v[38:41]
	v_mfma_f32_16x16x32_bf16 v[38:41], v[174:177], v[230:233], v[38:41]
	v_mfma_f32_16x16x32_bf16 v[42:45], v[164:167], v[230:233], v[42:45]
	v_mfma_f32_16x16x32_bf16 v[42:45], v[168:171], v[234:237], v[42:45]
	v_mfma_f32_16x16x32_bf16 v[46:49], v[160:163], v[234:237], v[46:49]
	v_mfma_f32_16x16x32_bf16 v[46:49], v[156:159], v[230:233], v[46:49]
	v_mfma_f32_16x16x32_bf16 v[30:33], v[156:159], v[238:241], v[30:33]
	v_mfma_f32_16x16x32_bf16 v[30:33], v[160:163], v[242:245], v[30:33]
	v_mfma_f32_16x16x32_bf16 v[26:29], v[168:171], v[242:245], v[26:29]
	v_mfma_f32_16x16x32_bf16 v[26:29], v[164:167], v[238:241], v[26:29]
	v_mfma_f32_16x16x32_bf16 v[22:25], v[174:177], v[238:241], v[22:25]
	v_mfma_f32_16x16x32_bf16 v[22:25], v[178:181], v[242:245], v[22:25]
	v_mfma_f32_16x16x32_bf16 v[18:21], v[186:189], v[242:245], v[18:21]
	v_mfma_f32_16x16x32_bf16 v[18:21], v[182:185], v[238:241], v[18:21]
	v_mfma_f32_16x16x32_bf16 v[2:5], v[182:185], v[246:249], v[2:5]
	v_mfma_f32_16x16x32_bf16 v[2:5], v[186:189], v[250:253], v[2:5]
	v_mfma_f32_16x16x32_bf16 v[6:9], v[178:181], v[250:253], v[6:9]
	v_mfma_f32_16x16x32_bf16 v[6:9], v[174:177], v[246:249], v[6:9]
	v_mfma_f32_16x16x32_bf16 v[10:13], v[164:167], v[246:249], v[10:13]
	v_mfma_f32_16x16x32_bf16 v[10:13], v[168:171], v[250:253], v[10:13]
	v_mfma_f32_16x16x32_bf16 v[14:17], v[160:163], v[250:253], v[14:17]
	v_mfma_f32_16x16x32_bf16 v[14:17], v[156:159], v[246:249], v[14:17]
	s_setprio 0
	s_waitcnt vmcnt(0)
	s_barrier
; #define PG8_STAGE(bufoff, gbase, voff) do { _Pragma("unroll") for (int _i = 0; _i < 2; ++_i) \
;         __builtin_amdgcn_global_load_lds((const unsigned*)((const char*)(gbase) + (voff)[_i]), (PG8_LAS unsigned*)(lds + (bufoff) + ldsw + _i * 8192), 16, 0, 0); } while (0)
; #define PG8_LDA(dst, b, h) do { _Pragma("unroll") for (int m = 0; m < 4; ++m) _Pragma("unroll") for (int k = 0; k < 2; ++k) dst[m][k] = *(const PG8_LAS bf16x8*)(lds + PG8_SA(b, h) + aoff + m * 2048 + k * 1024); } while (0)
; #define PG8_LDB(dst, b, h) do { _Pragma("unroll") for (int n = 0; n < 2; ++n) _Pragma("unroll") for (int k = 0; k < 2; ++k) dst[n][k] = *(const PG8_LAS bf16x8*)(lds + PG8_SB(b, h) + boff + n * 2048 + k * 1024); } while (0)
; #define PG8_MMA(ai, bj, At, Bt) do { __builtin_amdgcn_s_setprio(1); _Pragma("unroll") for (int m = 0; m < 4; ++m) _Pragma("unroll") for (int n = 0; n < 2; ++n) _Pragma("unroll") for (int k = 0; k < 2; ++k) \
;         acc[ai][bj][m][n] = __builtin_amdgcn_mfma_f32_16x16x32_bf16(Bt[n][k], At[m][k], acc[ai][bj][m][n], 0, 0, 0); __builtin_amdgcn_s_setprio(0); } while (0)
; #define PG8_WAIT_V(n) asm volatile("s_waitcnt vmcnt(" #n ")" ::: "memory")
; #define PG8_WAIT_L(n) asm volatile("s_waitcnt lgkmcnt(" #n ")" ::: "memory")
; #define PG8_BAR __builtin_amdgcn_s_barrier()
; #define PG8_SCHED __builtin_amdgcn_sched_barrier(0)
; template <class Epi, class Sched, bool ALIGN_EPI>
; __device__ __forceinline__ void gemm_phase(PG8_LAS unsigned char* lds, const Gemm g, const Sched& S, const Epi& E) {
;     ...
;             PG8_LDB(B0, 1, 0); PG8_LDB(B1, 1, 1); PG8_SCHED; PG8_LDA(At, 1, 0); PG8_STAGE(PG8_SA(0, 1), a2 + hstepA, voffA);
;             PG8_WAIT_V(8); PG8_WAIT_L(0); PG8_BAR; PG8_MMA(0, 0, At, B0); PG8_MMA(0, 1, At, B1); PG8_BAR; PG8_SCHED;
;             PG8_LDA(At, 1, 1); PG8_STAGE(PG8_SB(1, 0), b3, voffB); PG8_STAGE(PG8_SB(1, 1), b3 + hstepB, voffB); PG8_STAGE(PG8_SA(1, 0), a3, voffA);
;             PG8_WAIT_V(8); PG8_WAIT_L(0); PG8_BAR; PG8_MMA(1, 0, At, B0); PG8_MMA(1, 1, At, B1); PG8_BAR; PG8_SCHED;
;         }
	ds_read_b128 v[190:193], v155 offset:32768
	ds_read_b128 v[194:197], v155 offset:33792
	ds_read_b128 v[198:201], v155 offset:34816
	s_cmp_eq_u32 s49, 15
	s_cselect_b32 s28, s50, s28
	s_cselect_b32 s29, s51, s29
	s_add_i32 m0, s2, 0x2000
	s_nop 0
	global_load_lds_dwordx4 v132, s[28:29]
	ds_read_b128 v[202:205], v155 offset:35840
	ds_read_b128 v[206:209], v155 offset:36864
	ds_read_b128 v[210:213], v155 offset:37888
	s_add_u32 s30, s28, 0x20000
	s_addc_u32 s31, s29, 0
	s_add_i32 m0, s2, 0x3000
	s_nop 0
	global_load_lds_dwordx4 v132, s[30:31]
	ds_read_b128 v[214:217], v155 offset:38912
	ds_read_b128 v[218:221], v155 offset:39936
	ds_read_b128 v[156:159], v153 offset:32768
	s_add_u32 s30, s28, 0x80000
	s_addc_u32 s31, s29, 0
	s_add_i32 m0, s2, 0x6000
	s_nop 0
	global_load_lds_dwordx4 v132, s[30:31]
	ds_read_b128 v[160:163], v153 offset:33792
	ds_read_b128 v[164:167], v153 offset:34816
	ds_read_b128 v[168:171], v153 offset:35840
	s_add_u32 s30, s28, 0xa0000
	s_addc_u32 s31, s29, 0
	s_add_i32 m0, s2, 0x7000
	s_nop 0
	global_load_lds_dwordx4 v132, s[30:31]
	ds_read_b128 v[174:177], v153 offset:49152
	ds_read_b128 v[178:181], v153 offset:50176
	ds_read_b128 v[182:185], v153 offset:51200
	s_add_u32 s34, s28, 0x80
	s_addc_u32 s35, s29, 0
	s_add_i32 m0, s2, 0x8000
	s_nop 0
	global_load_lds_dwordx4 v136, s[34:35]
	ds_read_b128 v[186:189], v153 offset:52224
	ds_read_b128 v[222:225], v155 offset:49152
	ds_read_b128 v[226:229], v155 offset:50176
	s_add_u32 s30, s34, 0x20000
	s_addc_u32 s31, s35, 0
	s_add_i32 m0, s2, 0x9000
	s_nop 0
	global_load_lds_dwordx4 v136, s[30:31]
	ds_read_b128 v[230:233], v155 offset:51200
	ds_read_b128 v[234:237], v155 offset:52224
	ds_read_b128 v[238:241], v155 offset:53248
	s_add_u32 s30, s34, 0x80000
	s_addc_u32 s31, s35, 0
	s_add_i32 m0, s2, 0xc000
	s_nop 0
	global_load_lds_dwordx4 v136, s[30:31]
	ds_read_b128 v[242:245], v155 offset:54272
	ds_read_b128 v[246:249], v155 offset:55296
	ds_read_b128 v[250:253], v155 offset:56320
	s_add_u32 s30, s34, 0xa0000
	s_addc_u32 s31, s35, 0
	s_add_i32 m0, s2, 0xd000
	s_nop 0
	global_load_lds_dwordx4 v136, s[30:31]
	s_add_u32 s28, s28, 0x80
	s_addc_u32 s29, s29, 0
	s_waitcnt vmcnt(8) lgkmcnt(0)
	s_barrier
	s_setprio 1
	v_mfma_f32_16x16x32_bf16 v[126:129], v[156:159], v[190:193], v[126:129]
	v_mfma_f32_16x16x32_bf16 v[126:129], v[160:163], v[194:197], v[126:129]
	v_mfma_f32_16x16x32_bf16 v[122:125], v[168:171], v[194:197], v[122:125]
	v_mfma_f32_16x16x32_bf16 v[122:125], v[164:167], v[190:193], v[122:125]
	v_mfma_f32_16x16x32_bf16 v[118:121], v[174:177], v[190:193], v[118:121]
	v_mfma_f32_16x16x32_bf16 v[118:121], v[178:181], v[194:197], v[118:121]
	v_mfma_f32_16x16x32_bf16 v[114:117], v[186:189], v[194:197], v[114:117]
	v_mfma_f32_16x16x32_bf16 v[114:117], v[182:185], v[190:193], v[114:117]
	v_mfma_f32_16x16x32_bf16 v[98:101], v[182:185], v[198:201], v[98:101]
	v_mfma_f32_16x16x32_bf16 v[98:101], v[186:189], v[202:205], v[98:101]
	v_mfma_f32_16x16x32_bf16 v[102:105], v[178:181], v[202:205], v[102:105]
	v_mfma_f32_16x16x32_bf16 v[102:105], v[174:177], v[198:201], v[102:105]
	v_mfma_f32_16x16x32_bf16 v[106:109], v[164:167], v[198:201], v[106:109]
	v_mfma_f32_16x16x32_bf16 v[106:109], v[168:171], v[202:205], v[106:109]
	v_mfma_f32_16x16x32_bf16 v[110:113], v[160:163], v[202:205], v[110:113]
	v_mfma_f32_16x16x32_bf16 v[110:113], v[156:159], v[198:201], v[110:113]
	v_mfma_f32_16x16x32_bf16 v[94:97], v[156:159], v[206:209], v[94:97]
	v_mfma_f32_16x16x32_bf16 v[94:97], v[160:163], v[210:213], v[94:97]
	v_mfma_f32_16x16x32_bf16 v[90:93], v[168:171], v[210:213], v[90:93]
	v_mfma_f32_16x16x32_bf16 v[90:93], v[164:167], v[206:209], v[90:93]
	v_mfma_f32_16x16x32_bf16 v[86:89], v[174:177], v[206:209], v[86:89]
	v_mfma_f32_16x16x32_bf16 v[86:89], v[178:181], v[210:213], v[86:89]
	v_mfma_f32_16x16x32_bf16 v[82:85], v[186:189], v[210:213], v[82:85]
	v_mfma_f32_16x16x32_bf16 v[82:85], v[182:185], v[206:209], v[82:85]
	v_mfma_f32_16x16x32_bf16 v[66:69], v[182:185], v[214:217], v[66:69]
	v_mfma_f32_16x16x32_bf16 v[66:69], v[186:189], v[218:221], v[66:69]
	v_mfma_f32_16x16x32_bf16 v[70:73], v[178:181], v[218:221], v[70:73]
	v_mfma_f32_16x16x32_bf16 v[70:73], v[174:177], v[214:217], v[70:73]
	v_mfma_f32_16x16x32_bf16 v[74:77], v[164:167], v[214:217], v[74:77]
	v_mfma_f32_16x16x32_bf16 v[74:77], v[168:171], v[218:221], v[74:77]
	v_mfma_f32_16x16x32_bf16 v[78:81], v[160:163], v[218:221], v[78:81]
	v_mfma_f32_16x16x32_bf16 v[78:81], v[156:159], v[214:217], v[78:81]
	v_mfma_f32_16x16x32_bf16 v[62:65], v[156:159], v[222:225], v[62:65]
	v_mfma_f32_16x16x32_bf16 v[62:65], v[160:163], v[226:229], v[62:65]
	v_mfma_f32_16x16x32_bf16 v[58:61], v[168:171], v[226:229], v[58:61]
	v_mfma_f32_16x16x32_bf16 v[58:61], v[164:167], v[222:225], v[58:61]
	v_mfma_f32_16x16x32_bf16 v[54:57], v[174:177], v[222:225], v[54:57]
	v_mfma_f32_16x16x32_bf16 v[54:57], v[178:181], v[226:229], v[54:57]
	v_mfma_f32_16x16x32_bf16 v[50:53], v[186:189], v[226:229], v[50:53]
	v_mfma_f32_16x16x32_bf16 v[50:53], v[182:185], v[222:225], v[50:53]
	v_mfma_f32_16x16x32_bf16 v[34:37], v[182:185], v[230:233], v[34:37]
	v_mfma_f32_16x16x32_bf16 v[34:37], v[186:189], v[234:237], v[34:37]
	v_mfma_f32_16x16x32_bf16 v[38:41], v[178:181], v[234:237], v[38:41]
	v_mfma_f32_16x16x32_bf16 v[38:41], v[174:177], v[230:233], v[38:41]
	v_mfma_f32_16x16x32_bf16 v[42:45], v[164:167], v[230:233], v[42:45]
	v_mfma_f32_16x16x32_bf16 v[42:45], v[168:171], v[234:237], v[42:45]
	v_mfma_f32_16x16x32_bf16 v[46:49], v[160:163], v[234:237], v[46:49]
	v_mfma_f32_16x16x32_bf16 v[46:49], v[156:159], v[230:233], v[46:49]
	v_mfma_f32_16x16x32_bf16 v[30:33], v[156:159], v[238:241], v[30:33]
	v_mfma_f32_16x16x32_bf16 v[30:33], v[160:163], v[242:245], v[30:33]
	v_mfma_f32_16x16x32_bf16 v[26:29], v[168:171], v[242:245], v[26:29]
	v_mfma_f32_16x16x32_bf16 v[26:29], v[164:167], v[238:241], v[26:29]
	v_mfma_f32_16x16x32_bf16 v[22:25], v[174:177], v[238:241], v[22:25]
	v_mfma_f32_16x16x32_bf16 v[22:25], v[178:181], v[242:245], v[22:25]
	v_mfma_f32_16x16x32_bf16 v[18:21], v[186:189], v[242:245], v[18:21]
	v_mfma_f32_16x16x32_bf16 v[18:21], v[182:185], v[238:241], v[18:21]
	v_mfma_f32_16x16x32_bf16 v[2:5], v[182:185], v[246:249], v[2:5]
	v_mfma_f32_16x16x32_bf16 v[2:5], v[186:189], v[250:253], v[2:5]
	v_mfma_f32_16x16x32_bf16 v[6:9], v[178:181], v[250:253], v[6:9]
	v_mfma_f32_16x16x32_bf16 v[6:9], v[174:177], v[246:249], v[6:9]
	v_mfma_f32_16x16x32_bf16 v[10:13], v[164:167], v[246:249], v[10:13]
	v_mfma_f32_16x16x32_bf16 v[10:13], v[168:171], v[250:253], v[10:13]
	v_mfma_f32_16x16x32_bf16 v[14:17], v[160:163], v[250:253], v[14:17]
	v_mfma_f32_16x16x32_bf16 v[14:17], v[156:159], v[246:249], v[14:17]
	s_setprio 0
	s_waitcnt vmcnt(0)
	s_add_i32 s49, s49, 1
	s_cmp_lt_u32 s49, 16
	s_cbranch_scc0 .Lp8k_B_exit
	s_barrier
	s_branch .Lp8k_B_loop
; __device__ __forceinline__ unsigned cvt_pk_bf16(float lo, float hi) { unsigned r; asm volatile("v_cvt_pk_bf16_f32 %0, %1, %2" : "=v"(r) : "v"(lo), "v"(hi)); return r; }
; __device__ __forceinline__ float sigmoidf_(float x) { return __builtin_amdgcn_rcpf(1.0f + __builtin_amdgcn_exp2f(-1.4426950408889634f * x)); }
;     __device__ __forceinline__ void operator()(const f32x4 (&acc)[2][2][4][2], const Unit& u, int wr, int wc, int fr, int fq) const {
;         const int row0 = u.pm * BM + wr * 64 + fr, col0 = u.pn * HALF + wc * 32 + 8 * fq;
; #pragma unroll
;         for (int ai = 0; ai < 2; ++ai)
; #pragma unroll
;             for (int m = 0; m < 4; ++m) {
;                 const f32x4 g0 = acc[ai][0][m][0], g1 = acc[ai][0][m][1], u0 = acc[ai][1][m][0], u1 = acc[ai][1][m][1];
;                 u32x4 w;
;                 w.x = cvt_pk_bf16(g0[0] * sigmoidf_(g0[0]) * u0[0], g0[1] * sigmoidf_(g0[1]) * u0[1]); w.y = cvt_pk_bf16(g0[2] * sigmoidf_(g0[2]) * u0[2], g0[3] * sigmoidf_(g0[3]) * u0[3]);
;                 w.z = cvt_pk_bf16(g1[0] * sigmoidf_(g1[0]) * u1[0], g1[1] * sigmoidf_(g1[1]) * u1[1]); w.w = cvt_pk_bf16(g1[2] * sigmoidf_(g1[2]) * u1[2], g1[3] * sigmoidf_(g1[3]) * u1[3]);
;                 *(u32x4*)(O + (size_t)(row0 + ai * HALF + m * 16) * ldc + col0) = w; }
.Lp8k_B_exit:
.Lp8k_done:
.LBB0_904:
	v_mul_f32_e32 v157, 0xbfb8aa3b, v126
	v_exp_f32_e32 v157, v157
	v_mul_f32_e32 v158, 0xbfb8aa3b, v127
	v_exp_f32_e32 v159, v158
	v_lshl_or_b32 v158, s48, 7, v147
	v_add_f32_e32 v157, 1.0, v157
	v_rcp_f32_e32 v157, v157
	v_add_f32_e32 v159, 1.0, v159
	v_rcp_f32_e32 v160, v159
	v_lshl_add_u32 v156, s26, 8, v1
	v_mul_f32_e32 v126, v126, v157
	v_mul_f32_e32 v118, v126, v118
	v_mul_f32_e32 v126, v127, v160
	v_mul_f32_e32 v127, 0xbfb8aa3b, v128
	v_exp_f32_e32 v127, v127
	v_mul_f32_e32 v157, 0xbfb8aa3b, v129
	v_exp_f32_e32 v157, v157
	v_mul_f32_e32 v119, v126, v119
	v_add_f32_e32 v126, 1.0, v127
	v_rcp_f32_e32 v126, v126
	v_add_f32_e32 v127, 1.0, v157
	v_rcp_f32_e32 v127, v127
	v_cvt_pk_bf16_f32 v118, v118, v119
	v_mul_f32_e32 v119, v128, v126
	v_mul_f32_e32 v126, 0xbfb8aa3b, v122
	v_exp_f32_e32 v126, v126
	v_mul_f32_e32 v119, v119, v120
	v_mul_f32_e32 v120, v129, v127
	v_mul_f32_e32 v127, 0xbfb8aa3b, v123
	v_exp_f32_e32 v127, v127
	v_mul_f32_e32 v120, v120, v121
	v_add_f32_e32 v121, 1.0, v126
	v_rcp_f32_e32 v121, v121
	v_add_f32_e32 v126, 1.0, v127
	v_rcp_f32_e32 v126, v126
	v_cvt_pk_bf16_f32 v119, v119, v120
	v_mul_f32_e32 v120, v122, v121
	v_mul_f32_e32 v121, 0xbfb8aa3b, v124
	v_exp_f32_e32 v121, v121
	v_mul_f32_e32 v122, 0xbfb8aa3b, v125
	v_exp_f32_e32 v122, v122
	v_mul_f32_e32 v114, v120, v114
	v_mul_f32_e32 v120, v123, v126
	v_mul_f32_e32 v115, v120, v115
	v_add_f32_e32 v120, 1.0, v121
	v_rcp_f32_e32 v121, v120
	v_add_f32_e32 v120, 1.0, v122
	v_rcp_f32_e32 v122, v120
	v_cvt_pk_bf16_f32 v120, v114, v115
	v_mul_f32_e32 v114, v124, v121
	v_mul_f32_e32 v124, 0xbfb8aa3b, v110
	v_mul_f32_e32 v115, v125, v122
	v_exp_f32_e32 v124, v124
	v_mul_f32_e32 v125, 0xbfb8aa3b, v111
	v_exp_f32_e32 v125, v125
	v_mul_f32_e32 v114, v114, v116
	v_add_f32_e32 v124, 1.0, v124
	v_rcp_f32_e32 v124, v124
	v_add_f32_e32 v125, 1.0, v125
	v_rcp_f32_e32 v125, v125
	v_mul_f32_e32 v115, v115, v117
	v_mul_f32_e32 v110, v110, v124
	v_mul_f32_e32 v102, v110, v102
	v_mul_f32_e32 v110, v111, v125
	v_mul_f32_e32 v111, 0xbfb8aa3b, v112
	v_ashrrev_i32_e32 v159, 31, v158
	v_cvt_pk_bf16_f32 v121, v114, v115
	v_mov_b64_e32 v[114:115], s[66:67]
	v_exp_f32_e32 v111, v111
	v_mad_i64_i32 v[122:123], s[28:29], v156, s47, v[114:115]
	v_lshlrev_b64 v[116:117], 1, v[158:159]
	v_lshl_add_u64 v[122:123], v[122:123], 0, v[116:117]
	global_store_dwordx4 v[122:123], v[118:121], off
	v_mul_f32_e32 v103, v110, v103
	v_add_f32_e32 v110, 1.0, v111
	v_mul_f32_e32 v118, 0xbfb8aa3b, v113
	v_exp_f32_e32 v118, v118
	v_rcp_f32_e32 v110, v110
	v_cvt_pk_bf16_f32 v102, v102, v103
	s_andn2_b64 vcc, exec, s[0:1]
	v_add_f32_e32 v111, 1.0, v118
	v_rcp_f32_e32 v111, v111
	v_mul_f32_e32 v103, v112, v110
	v_mul_f32_e32 v110, 0xbfb8aa3b, v106
	v_exp_f32_e32 v110, v110
	v_mul_f32_e32 v103, v103, v104
	v_mul_f32_e32 v104, v113, v111
	v_mul_f32_e32 v111, 0xbfb8aa3b, v107
	v_exp_f32_e32 v111, v111
	v_mul_f32_e32 v104, v104, v105
	v_add_f32_e32 v105, 1.0, v110
	v_rcp_f32_e32 v105, v105
	v_add_f32_e32 v110, 1.0, v111
	v_rcp_f32_e32 v110, v110
	v_cvt_pk_bf16_f32 v103, v103, v104
	v_mul_f32_e32 v104, v106, v105
	v_mul_f32_e32 v105, 0xbfb8aa3b, v108
	v_exp_f32_e32 v105, v105
	v_mul_f32_e32 v106, 0xbfb8aa3b, v109
	v_exp_f32_e32 v106, v106
	v_mul_f32_e32 v98, v104, v98
	v_mul_f32_e32 v104, v107, v110
	v_mul_f32_e32 v99, v104, v99
	v_add_f32_e32 v104, 1.0, v105
	v_rcp_f32_e32 v105, v104
	v_add_f32_e32 v104, 1.0, v106
	v_rcp_f32_e32 v106, v104
	v_cvt_pk_bf16_f32 v104, v98, v99
	v_mul_f32_e32 v98, v108, v105
	v_mul_f32_e32 v98, v98, v100
	v_mul_f32_e32 v99, v109, v106
	v_mul_f32_e32 v100, 0xbfb8aa3b, v94
	v_mul_f32_e32 v99, v99, v101
	v_exp_f32_e32 v100, v100
	v_mul_f32_e32 v101, 0xbfb8aa3b, v95
	v_exp_f32_e32 v101, v101
	v_cvt_pk_bf16_f32 v105, v98, v99
	v_add_f32_e32 v100, 1.0, v100
	v_rcp_f32_e32 v100, v100
	v_add_f32_e32 v101, 1.0, v101
	v_rcp_f32_e32 v101, v101
	v_or_b32_e32 v98, 16, v156
	v_mul_f32_e32 v94, v94, v100
	v_mul_f32_e32 v86, v94, v86
	v_mul_f32_e32 v94, v95, v101
	v_mul_f32_e32 v95, 0xbfb8aa3b, v96
	v_exp_f32_e32 v95, v95
	v_mad_i64_i32 v[98:99], s[28:29], v98, s47, v[114:115]
	v_lshl_add_u64 v[98:99], v[98:99], 0, v[116:117]
	global_store_dwordx4 v[98:99], v[102:105], off
	v_mul_f32_e32 v98, 0xbfb8aa3b, v97
	v_exp_f32_e32 v98, v98
	v_mul_f32_e32 v87, v94, v87
	v_add_f32_e32 v94, 1.0, v95
	v_rcp_f32_e32 v94, v94
	v_add_f32_e32 v95, 1.0, v98
	v_rcp_f32_e32 v95, v95
	v_cvt_pk_bf16_f32 v86, v86, v87
	v_mul_f32_e32 v87, v96, v94
	v_mul_f32_e32 v94, 0xbfb8aa3b, v90
	v_exp_f32_e32 v94, v94
	v_mul_f32_e32 v87, v87, v88
	v_mul_f32_e32 v88, v97, v95
	v_mul_f32_e32 v95, 0xbfb8aa3b, v91
	v_exp_f32_e32 v95, v95
	v_mul_f32_e32 v88, v88, v89
	v_add_f32_e32 v89, 1.0, v94
	v_rcp_f32_e32 v89, v89
	v_add_f32_e32 v94, 1.0, v95
	v_rcp_f32_e32 v94, v94
	v_cvt_pk_bf16_f32 v87, v87, v88
	v_mul_f32_e32 v88, v90, v89
	v_mul_f32_e32 v89, 0xbfb8aa3b, v92
	v_exp_f32_e32 v89, v89
	v_mul_f32_e32 v90, 0xbfb8aa3b, v93
	v_exp_f32_e32 v90, v90
	v_mul_f32_e32 v82, v88, v82
	v_mul_f32_e32 v88, v91, v94
	v_mul_f32_e32 v83, v88, v83
	v_add_f32_e32 v88, 1.0, v89
	v_rcp_f32_e32 v89, v88
	v_add_f32_e32 v88, 1.0, v90
	v_rcp_f32_e32 v90, v88
	v_cvt_pk_bf16_f32 v88, v82, v83
	v_mul_f32_e32 v82, v92, v89
	v_mul_f32_e32 v82, v82, v84
	v_mul_f32_e32 v83, v93, v90
	v_mul_f32_e32 v84, 0xbfb8aa3b, v78
	v_mul_f32_e32 v83, v83, v85
	v_exp_f32_e32 v84, v84
	v_mul_f32_e32 v85, 0xbfb8aa3b, v79
	v_exp_f32_e32 v85, v85
	v_cvt_pk_bf16_f32 v89, v82, v83
	v_add_f32_e32 v84, 1.0, v84
	v_rcp_f32_e32 v84, v84
	v_add_f32_e32 v85, 1.0, v85
	v_rcp_f32_e32 v85, v85
	v_or_b32_e32 v82, 32, v156
	v_mul_f32_e32 v78, v78, v84
	v_mul_f32_e32 v70, v78, v70
; __device__ __forceinline__ unsigned cvt_pk_bf16(float lo, float hi) { unsigned r; asm volatile("v_cvt_pk_bf16_f32 %0, %1, %2" : "=v"(r) : "v"(lo), "v"(hi)); return r; }
; __device__ __forceinline__ float sigmoidf_(float x) { return __builtin_amdgcn_rcpf(1.0f + __builtin_amdgcn_exp2f(-1.4426950408889634f * x)); }
;     __device__ __forceinline__ void operator()(const f32x4 (&acc)[2][2][4][2], const Unit& u, int wr, int wc, int fr, int fq) const {
;     ...
;         for (int ai = 0; ai < 2; ++ai)
; #pragma unroll
;             for (int m = 0; m < 4; ++m) {
;                 const f32x4 g0 = acc[ai][0][m][0], g1 = acc[ai][0][m][1], u0 = acc[ai][1][m][0], u1 = acc[ai][1][m][1];
;                 u32x4 w;
;                 w.x = cvt_pk_bf16(g0[0] * sigmoidf_(g0[0]) * u0[0], g0[1] * sigmoidf_(g0[1]) * u0[1]); w.y = cvt_pk_bf16(g0[2] * sigmoidf_(g0[2]) * u0[2], g0[3] * sigmoidf_(g0[3]) * u0[3]);
;                 w.z = cvt_pk_bf16(g1[0] * sigmoidf_(g1[0]) * u1[0], g1[1] * sigmoidf_(g1[1]) * u1[1]); w.w = cvt_pk_bf16(g1[2] * sigmoidf_(g1[2]) * u1[2], g1[3] * sigmoidf_(g1[3]) * u1[3]);
;                 *(u32x4*)(O + (size_t)(row0 + ai * HALF + m * 16) * ldc + col0) = w; }
	v_mul_f32_e32 v78, v79, v85
	v_mul_f32_e32 v79, 0xbfb8aa3b, v80
	v_exp_f32_e32 v79, v79
	v_mad_i64_i32 v[82:83], s[28:29], v82, s47, v[114:115]
	v_lshl_add_u64 v[82:83], v[82:83], 0, v[116:117]
	global_store_dwordx4 v[82:83], v[86:89], off
	v_mul_f32_e32 v82, 0xbfb8aa3b, v81
	v_exp_f32_e32 v82, v82
	v_mul_f32_e32 v71, v78, v71
	v_add_f32_e32 v78, 1.0, v79
	v_rcp_f32_e32 v78, v78
	v_add_f32_e32 v79, 1.0, v82
	v_rcp_f32_e32 v79, v79
	v_cvt_pk_bf16_f32 v70, v70, v71
	v_mul_f32_e32 v71, v80, v78
	v_mul_f32_e32 v78, 0xbfb8aa3b, v74
	v_exp_f32_e32 v78, v78
	v_mul_f32_e32 v71, v71, v72
	v_mul_f32_e32 v72, v81, v79
	v_mul_f32_e32 v79, 0xbfb8aa3b, v75
	v_exp_f32_e32 v79, v79
	v_mul_f32_e32 v72, v72, v73
	v_add_f32_e32 v73, 1.0, v78
	v_rcp_f32_e32 v73, v73
	v_add_f32_e32 v78, 1.0, v79
	v_rcp_f32_e32 v78, v78
	v_cvt_pk_bf16_f32 v71, v71, v72
	v_mul_f32_e32 v72, v74, v73
	v_mul_f32_e32 v73, 0xbfb8aa3b, v76
	v_exp_f32_e32 v73, v73
	v_mul_f32_e32 v74, 0xbfb8aa3b, v77
	v_exp_f32_e32 v74, v74
	v_mul_f32_e32 v66, v72, v66
	v_mul_f32_e32 v72, v75, v78
	v_mul_f32_e32 v67, v72, v67
	v_add_f32_e32 v72, 1.0, v73
	v_rcp_f32_e32 v73, v72
	v_add_f32_e32 v72, 1.0, v74
	v_rcp_f32_e32 v74, v72
	v_cvt_pk_bf16_f32 v72, v66, v67
	v_mul_f32_e32 v66, v76, v73
	v_mul_f32_e32 v66, v66, v68
	v_mul_f32_e32 v67, v77, v74
	v_mul_f32_e32 v68, 0xbfb8aa3b, v62
	v_mul_f32_e32 v67, v67, v69
	v_exp_f32_e32 v68, v68
	v_mul_f32_e32 v69, 0xbfb8aa3b, v63
	v_cvt_pk_bf16_f32 v73, v66, v67
	v_or_b32_e32 v66, 48, v156
	v_exp_f32_e32 v69, v69
	v_mad_i64_i32 v[66:67], s[28:29], v66, s47, v[114:115]
	v_lshl_add_u64 v[66:67], v[66:67], 0, v[116:117]
	global_store_dwordx4 v[66:67], v[70:73], off
	v_add_f32_e32 v66, 1.0, v68
	v_rcp_f32_e32 v66, v66
	v_add_f32_e32 v67, 1.0, v69
	v_rcp_f32_e32 v67, v67
	v_add_u32_e32 v68, 0x80, v156
	v_mul_f32_e32 v62, v62, v66
	v_mul_f32_e32 v54, v62, v54
	v_mul_f32_e32 v62, v63, v67
	v_mul_f32_e32 v63, 0xbfb8aa3b, v64
	v_exp_f32_e32 v63, v63
	v_mul_f32_e32 v66, 0xbfb8aa3b, v65
	v_exp_f32_e32 v66, v66
	v_mul_f32_e32 v55, v62, v55
	v_add_f32_e32 v62, 1.0, v63
	v_rcp_f32_e32 v62, v62
	v_add_f32_e32 v63, 1.0, v66
	v_rcp_f32_e32 v63, v63
	v_cvt_pk_bf16_f32 v54, v54, v55
	v_mul_f32_e32 v55, v64, v62
	v_mul_f32_e32 v62, 0xbfb8aa3b, v58
	v_exp_f32_e32 v62, v62
	v_mul_f32_e32 v55, v55, v56
	v_mul_f32_e32 v56, v65, v63
	v_mul_f32_e32 v63, 0xbfb8aa3b, v59
	v_exp_f32_e32 v63, v63
	v_mul_f32_e32 v56, v56, v57
	v_add_f32_e32 v57, 1.0, v62
	v_rcp_f32_e32 v57, v57
	v_add_f32_e32 v62, 1.0, v63
	v_rcp_f32_e32 v62, v62
	v_cvt_pk_bf16_f32 v55, v55, v56
	v_mul_f32_e32 v56, v58, v57
	v_mul_f32_e32 v57, 0xbfb8aa3b, v60
	v_exp_f32_e32 v57, v57
	v_mul_f32_e32 v58, 0xbfb8aa3b, v61
	v_exp_f32_e32 v58, v58
	v_mul_f32_e32 v50, v56, v50
	v_mul_f32_e32 v56, v59, v62
	v_mul_f32_e32 v51, v56, v51
	v_add_f32_e32 v56, 1.0, v57
	v_rcp_f32_e32 v57, v56
	v_add_f32_e32 v56, 1.0, v58
	v_rcp_f32_e32 v58, v56
	v_cvt_pk_bf16_f32 v56, v50, v51
	v_mul_f32_e32 v50, v60, v57
	v_mul_f32_e32 v50, v50, v52
	v_mul_f32_e32 v51, v61, v58
	v_mul_f32_e32 v52, 0xbfb8aa3b, v46
	v_mul_f32_e32 v51, v51, v53
	v_exp_f32_e32 v52, v52
	v_mul_f32_e32 v53, 0xbfb8aa3b, v47
	v_exp_f32_e32 v53, v53
	v_cvt_pk_bf16_f32 v57, v50, v51
	v_add_f32_e32 v52, 1.0, v52
	v_rcp_f32_e32 v52, v52
	v_add_f32_e32 v53, 1.0, v53
	v_rcp_f32_e32 v53, v53
	v_mad_i64_i32 v[50:51], s[28:29], v68, s47, v[114:115]
	v_mul_f32_e32 v46, v46, v52
	v_mul_f32_e32 v38, v46, v38
	v_mul_f32_e32 v46, v47, v53
	v_mul_f32_e32 v47, 0xbfb8aa3b, v48
	v_exp_f32_e32 v47, v47
	v_lshl_add_u64 v[50:51], v[50:51], 0, v[116:117]
	global_store_dwordx4 v[50:51], v[54:57], off
	v_mul_f32_e32 v50, 0xbfb8aa3b, v49
	v_exp_f32_e32 v50, v50
	v_mul_f32_e32 v39, v46, v39
	v_add_f32_e32 v46, 1.0, v47
	v_rcp_f32_e32 v46, v46
	v_add_f32_e32 v47, 1.0, v50
	v_rcp_f32_e32 v47, v47
	v_cvt_pk_bf16_f32 v38, v38, v39
	v_mul_f32_e32 v39, v48, v46
	v_mul_f32_e32 v46, 0xbfb8aa3b, v42
	v_exp_f32_e32 v46, v46
	v_mul_f32_e32 v39, v39, v40
	v_mul_f32_e32 v40, v49, v47
	v_mul_f32_e32 v47, 0xbfb8aa3b, v43
	v_exp_f32_e32 v47, v47
	v_mul_f32_e32 v40, v40, v41
	v_add_f32_e32 v41, 1.0, v46
	v_rcp_f32_e32 v41, v41
	v_add_f32_e32 v46, 1.0, v47
	v_rcp_f32_e32 v46, v46
; __device__ __forceinline__ unsigned cvt_pk_bf16(float lo, float hi) { unsigned r; asm volatile("v_cvt_pk_bf16_f32 %0, %1, %2" : "=v"(r) : "v"(lo), "v"(hi)); return r; }
; __device__ __forceinline__ float sigmoidf_(float x) { return __builtin_amdgcn_rcpf(1.0f + __builtin_amdgcn_exp2f(-1.4426950408889634f * x)); }
; #define PG8_WAIT_V(n) asm volatile("s_waitcnt vmcnt(" #n ")" ::: "memory")
; #define PG8_BAR __builtin_amdgcn_s_barrier()
;     __device__ __forceinline__ void operator()(const f32x4 (&acc)[2][2][4][2], const Unit& u, int wr, int wc, int fr, int fq) const {
;     ...
;         for (int ai = 0; ai < 2; ++ai)
; #pragma unroll
;             for (int m = 0; m < 4; ++m) {
;                 const f32x4 g0 = acc[ai][0][m][0], g1 = acc[ai][0][m][1], u0 = acc[ai][1][m][0], u1 = acc[ai][1][m][1];
;                 u32x4 w;
;                 w.x = cvt_pk_bf16(g0[0] * sigmoidf_(g0[0]) * u0[0], g0[1] * sigmoidf_(g0[1]) * u0[1]); w.y = cvt_pk_bf16(g0[2] * sigmoidf_(g0[2]) * u0[2], g0[3] * sigmoidf_(g0[3]) * u0[3]);
;                 w.z = cvt_pk_bf16(g1[0] * sigmoidf_(g1[0]) * u1[0], g1[1] * sigmoidf_(g1[1]) * u1[1]); w.w = cvt_pk_bf16(g1[2] * sigmoidf_(g1[2]) * u1[2], g1[3] * sigmoidf_(g1[3]) * u1[3]);
;                 *(u32x4*)(O + (size_t)(row0 + ai * HALF + m * 16) * ldc + col0) = w; }
; template <class Epi, class Sched, bool ALIGN_EPI>
; __device__ __forceinline__ void gemm_phase(PG8_LAS unsigned char* lds, const Gemm g, const Sched& S, const Epi& E) {
;     ...
;         if constexpr (ALIGN_EPI) { if (wr == 1) PG8_BAR; }
;     }
;     PG8_WAIT_V(0);
;     if constexpr (!ALIGN_EPI) { if (wr == 0) PG8_BAR; }
;     PG8_BAR;
	v_cvt_pk_bf16_f32 v39, v39, v40
	v_mul_f32_e32 v40, v42, v41
	v_mul_f32_e32 v41, 0xbfb8aa3b, v44
	v_exp_f32_e32 v41, v41
	v_mul_f32_e32 v42, 0xbfb8aa3b, v45
	v_exp_f32_e32 v42, v42
	v_mul_f32_e32 v34, v40, v34
	v_mul_f32_e32 v40, v43, v46
	v_mul_f32_e32 v35, v40, v35
	v_add_f32_e32 v40, 1.0, v41
	v_rcp_f32_e32 v41, v40
	v_add_f32_e32 v40, 1.0, v42
	v_rcp_f32_e32 v42, v40
	v_cvt_pk_bf16_f32 v40, v34, v35
	v_mul_f32_e32 v34, v44, v41
	v_mul_f32_e32 v34, v34, v36
	v_mul_f32_e32 v35, v45, v42
	v_mul_f32_e32 v36, 0xbfb8aa3b, v30
	v_mul_f32_e32 v35, v35, v37
	v_exp_f32_e32 v36, v36
	v_mul_f32_e32 v37, 0xbfb8aa3b, v31
	v_exp_f32_e32 v37, v37
	v_cvt_pk_bf16_f32 v41, v34, v35
	v_add_f32_e32 v36, 1.0, v36
	v_rcp_f32_e32 v36, v36
	v_add_f32_e32 v37, 1.0, v37
	v_rcp_f32_e32 v37, v37
	v_add_u32_e32 v34, 0x90, v156
	v_mul_f32_e32 v30, v30, v36
	v_mul_f32_e32 v22, v30, v22
	v_mul_f32_e32 v30, v31, v37
	v_mul_f32_e32 v31, 0xbfb8aa3b, v32
	v_exp_f32_e32 v31, v31
	v_mad_i64_i32 v[34:35], s[28:29], v34, s47, v[114:115]
	v_lshl_add_u64 v[34:35], v[34:35], 0, v[116:117]
	global_store_dwordx4 v[34:35], v[38:41], off
	v_mul_f32_e32 v34, 0xbfb8aa3b, v33
	v_exp_f32_e32 v34, v34
	v_mul_f32_e32 v23, v30, v23
	v_add_f32_e32 v30, 1.0, v31
	v_rcp_f32_e32 v30, v30
	v_add_f32_e32 v31, 1.0, v34
	v_rcp_f32_e32 v31, v31
	v_cvt_pk_bf16_f32 v22, v22, v23
	v_mul_f32_e32 v23, v32, v30
	v_mul_f32_e32 v30, 0xbfb8aa3b, v26
	v_exp_f32_e32 v30, v30
	v_mul_f32_e32 v23, v23, v24
	v_mul_f32_e32 v24, v33, v31
	v_mul_f32_e32 v31, 0xbfb8aa3b, v27
	v_exp_f32_e32 v31, v31
	v_mul_f32_e32 v24, v24, v25
	v_add_f32_e32 v25, 1.0, v30
	v_rcp_f32_e32 v25, v25
	v_add_f32_e32 v30, 1.0, v31
	v_rcp_f32_e32 v30, v30
	v_cvt_pk_bf16_f32 v23, v23, v24
	v_mul_f32_e32 v24, v26, v25
	v_mul_f32_e32 v25, 0xbfb8aa3b, v28
	v_exp_f32_e32 v25, v25
	v_mul_f32_e32 v26, 0xbfb8aa3b, v29
	v_exp_f32_e32 v26, v26
	v_mul_f32_e32 v18, v24, v18
	v_mul_f32_e32 v24, v27, v30
	v_mul_f32_e32 v19, v24, v19
	v_add_f32_e32 v24, 1.0, v25
	v_rcp_f32_e32 v25, v24
	v_add_f32_e32 v24, 1.0, v26
	v_rcp_f32_e32 v26, v24
	v_cvt_pk_bf16_f32 v24, v18, v19
	v_mul_f32_e32 v18, v28, v25
	v_mul_f32_e32 v18, v18, v20
	v_mul_f32_e32 v19, v29, v26
	v_mul_f32_e32 v20, 0xbfb8aa3b, v14
	v_mul_f32_e32 v19, v19, v21
	v_exp_f32_e32 v20, v20
	v_mul_f32_e32 v21, 0xbfb8aa3b, v15
	v_exp_f32_e32 v21, v21
	v_cvt_pk_bf16_f32 v25, v18, v19
	v_add_f32_e32 v20, 1.0, v20
	v_rcp_f32_e32 v20, v20
	v_add_f32_e32 v21, 1.0, v21
	v_rcp_f32_e32 v21, v21
	v_add_u32_e32 v18, 0xa0, v156
	v_mul_f32_e32 v14, v14, v20
	v_mul_f32_e32 v6, v14, v6
	v_mul_f32_e32 v14, v15, v21
	v_mul_f32_e32 v15, 0xbfb8aa3b, v16
	v_exp_f32_e32 v15, v15
	v_mad_i64_i32 v[18:19], s[28:29], v18, s47, v[114:115]
	v_lshl_add_u64 v[18:19], v[18:19], 0, v[116:117]
	global_store_dwordx4 v[18:19], v[22:25], off
	v_mul_f32_e32 v18, 0xbfb8aa3b, v17
	v_exp_f32_e32 v18, v18
	v_mul_f32_e32 v7, v14, v7
	v_add_f32_e32 v14, 1.0, v15
	v_rcp_f32_e32 v14, v14
	v_add_f32_e32 v15, 1.0, v18
	v_rcp_f32_e32 v15, v15
	v_cvt_pk_bf16_f32 v6, v6, v7
	v_mul_f32_e32 v7, v16, v14
	v_mul_f32_e32 v14, 0xbfb8aa3b, v10
	v_exp_f32_e32 v14, v14
	v_mul_f32_e32 v7, v7, v8
	v_mul_f32_e32 v8, v17, v15
	v_mul_f32_e32 v15, 0xbfb8aa3b, v11
	v_exp_f32_e32 v15, v15
	v_mul_f32_e32 v8, v8, v9
	v_add_f32_e32 v9, 1.0, v14
	v_rcp_f32_e32 v9, v9
	v_add_f32_e32 v14, 1.0, v15
	v_rcp_f32_e32 v14, v14
	v_cvt_pk_bf16_f32 v7, v7, v8
	v_mul_f32_e32 v8, v10, v9
	v_mul_f32_e32 v9, 0xbfb8aa3b, v12
	v_exp_f32_e32 v9, v9
	v_mul_f32_e32 v10, 0xbfb8aa3b, v13
	v_exp_f32_e32 v10, v10
	v_mul_f32_e32 v2, v8, v2
	v_mul_f32_e32 v8, v11, v14
	v_mul_f32_e32 v3, v8, v3
	v_add_f32_e32 v8, 1.0, v9
	v_rcp_f32_e32 v9, v8
	v_add_f32_e32 v8, 1.0, v10
	v_rcp_f32_e32 v10, v8
	v_cvt_pk_bf16_f32 v8, v2, v3
	v_mul_f32_e32 v2, v12, v9
	v_mul_f32_e32 v2, v2, v4
	v_mul_f32_e32 v3, v13, v10
	v_mul_f32_e32 v3, v3, v5
	v_cvt_pk_bf16_f32 v9, v2, v3
	v_add_u32_e32 v2, 0xb0, v156
	v_mad_i64_i32 v[2:3], s[28:29], v2, s47, v[114:115]
	v_lshl_add_u64 v[2:3], v[2:3], 0, v[116:117]
	s_mov_b64 s[0:1], -1
	global_store_dwordx4 v[2:3], v[6:9], off
	s_cbranch_vccnz .LBB0_897
	s_branch .LBB0_896
.LBB0_907:
	s_waitcnt lgkmcnt(0)
	s_waitcnt vmcnt(0)
	s_barrier
